# combination: first-map prefetch in the second map's epilogue + early accumulator zeroing in GEMM prologues + first PV MFMA hoisted into the tail of the row-max chain (canonicalising max ops dropped)
# speedup vs baseline: 1.0032x; 1.0032x over previous
.Ldattn_rare:
	ds_read_b64_tr_b16 v[100:101], v177 offset:33792
	ds_read_b64_tr_b16 v[102:103], v177 offset:34304
	ds_read_b64_tr_b16 v[162:163], v177 offset:33280
	v_max_f32_e32 v0, v0, v0
	v_max_f32_e32 v2, 0, v0
	v_exp_f32_e64 v0, -v2
	v_add_f32_e32 v175, v175, v2
	v_sub_f32_e32 v99, v99, v2
	v_sub_f32_e32 v98, v98, v2
	s_waitcnt lgkmcnt(7)
	v_mfma_f32_32x32x16_bf16 v[36:51], v[156:159], v[144:147], v[36:51]
	v_sub_f32_e32 v97, v97, v2
	v_sub_f32_e32 v96, v96, v2
	v_sub_f32_e32 v95, v95, v2
	v_sub_f32_e32 v94, v94, v2
	v_sub_f32_e32 v93, v93, v2
	v_sub_f32_e32 v92, v92, v2
	v_sub_f32_e32 v91, v91, v2
	s_waitcnt lgkmcnt(5)
	v_mfma_f32_32x32x16_bf16 v[20:35], v[152:155], v[144:147], v[20:35]
	v_sub_f32_e32 v90, v90, v2
	v_sub_f32_e32 v89, v89, v2
	v_sub_f32_e32 v88, v88, v2
	v_sub_f32_e32 v87, v87, v2
	v_sub_f32_e32 v86, v86, v2
	v_sub_f32_e32 v85, v85, v2
	v_sub_f32_e32 v84, v84, v2
	s_waitcnt lgkmcnt(1)
	v_mfma_f32_32x32x16_bf16 v[52:67], v[100:103], v[140:143], v[52:67]
	ds_read_b64_tr_b16 v[100:101], v177 offset:37888
	ds_read_b64_tr_b16 v[102:103], v177 offset:38400
	ds_read_b64_tr_b16 v[158:159], v177 offset:37376
	v_sub_f32_e32 v83, v83, v2
	v_sub_f32_e32 v82, v82, v2
	v_sub_f32_e32 v81, v81, v2
	v_sub_f32_e32 v80, v80, v2
	v_sub_f32_e32 v79, v79, v2
	v_sub_f32_e32 v78, v78, v2
	v_mfma_f32_32x32x16_bf16 v[4:19], v[148:151], v[144:147], v[4:19]
	v_sub_f32_e32 v77, v77, v2
	v_sub_f32_e32 v76, v76, v2
	v_sub_f32_e32 v75, v75, v2
	v_sub_f32_e32 v74, v74, v2
	v_sub_f32_e32 v73, v73, v2
	v_sub_f32_e32 v72, v72, v2
	v_sub_f32_e32 v71, v71, v2
	s_waitcnt lgkmcnt(1)
	v_mfma_f32_32x32x16_bf16 v[36:51], v[100:103], v[140:143], v[36:51]
	ds_read_b64_tr_b16 v[100:101], v177 offset:41984
	ds_read_b64_tr_b16 v[102:103], v177 offset:42496
	ds_read_b64_tr_b16 v[154:155], v177 offset:41472
	v_sub_f32_e32 v70, v70, v2
	v_sub_f32_e32 v69, v69, v2
	v_sub_f32_e32 v68, v68, v2
	v_mov_b32_e32 v2, v1
	v_mov_b32_e32 v3, v1
	v_mul_f32_e32 v173, v173, v0
	s_waitcnt lgkmcnt(1)
	v_mfma_f32_32x32x16_bf16 v[20:35], v[100:103], v[140:143], v[20:35]
	ds_read_b64_tr_b16 v[100:101], v177 offset:46080
	ds_read_b64_tr_b16 v[102:103], v177 offset:46592
	ds_read_b64_tr_b16 v[150:151], v177 offset:45568
	s_waitcnt lgkmcnt(1)
	v_mfma_f32_32x32x16_bf16 v[4:19], v[100:103], v[140:143], v[4:19]
	ds_read_b64_tr_b16 v[100:101], v177 offset:34816
	ds_read_b64_tr_b16 v[102:103], v177 offset:35328
	ds_read_b64_tr_b16 v[104:105], v177 offset:35840
	ds_read_b64_tr_b16 v[106:107], v177 offset:36352
	s_waitcnt lgkmcnt(2)
	v_mfma_f32_32x32x16_bf16 v[52:67], v[100:103], v[136:139], v[52:67]
	ds_read_b64_tr_b16 v[100:101], v177 offset:38912
	ds_read_b64_tr_b16 v[102:103], v177 offset:39424
	ds_read_b64_tr_b16 v[108:109], v177 offset:39936
	ds_read_b64_tr_b16 v[110:111], v177 offset:40448
	s_waitcnt lgkmcnt(2)
	v_mfma_f32_32x32x16_bf16 v[36:51], v[100:103], v[136:139], v[36:51]
	ds_read_b64_tr_b16 v[100:101], v177 offset:43008
	ds_read_b64_tr_b16 v[102:103], v177 offset:43520
	ds_read_b64_tr_b16 v[112:113], v177 offset:44032
	ds_read_b64_tr_b16 v[114:115], v177 offset:44544
	ds_read_b64_tr_b16 v[160:161], v177 offset:32768
	ds_read_b64_tr_b16 v[156:157], v177 offset:36864
	ds_read_b64_tr_b16 v[152:153], v177 offset:40960
	ds_read_b64_tr_b16 v[148:149], v177 offset:45056
	s_waitcnt lgkmcnt(6)
	v_mfma_f32_32x32x16_bf16 v[20:35], v[100:103], v[136:139], v[20:35]
	v_mfma_f32_32x32x16_bf16 v[52:67], v[104:107], v[132:135], v[52:67]
	ds_read_b64_tr_b16 v[100:101], v177 offset:47104
	ds_read_b64_tr_b16 v[102:103], v177 offset:47616
	ds_read_b64_tr_b16 v[104:105], v177 offset:48128
	ds_read_b64_tr_b16 v[106:107], v177 offset:48640
	s_waitcnt lgkmcnt(2)
	v_mfma_f32_32x32x16_bf16 v[4:19], v[100:103], v[136:139], v[4:19]
	s_nop 5
	v_mul_f32_e64 v66, v0, v66
	v_mul_f32_e64 v67, v0, v67
	v_mul_f32_e64 v64, v0, v64
	v_mul_f32_e64 v65, v0, v65
	v_mul_f32_e64 v62, v0, v62
	v_mul_f32_e64 v63, v0, v63
	v_pk_mul_f32 v[60:61], v[0:1], v[60:61] op_sel_hi:[0,1]
	v_pk_mul_f32 v[58:59], v[0:1], v[58:59] op_sel_hi:[0,1]
	v_pk_mul_f32 v[56:57], v[0:1], v[56:57] op_sel_hi:[0,1]
	v_pk_mul_f32 v[54:55], v[0:1], v[54:55] op_sel_hi:[0,1]
	v_mfma_f32_32x32x16_bf16 v[36:51], v[108:111], v[132:135], v[36:51]
	v_mul_f32_e64 v52, v0, v52
	v_mul_f32_e64 v53, v0, v53
	v_xor_b32_e32 v100, 0x80000000, v175
	v_mov_b32_e32 v101, v100
	v_mov_b32_e32 v102, v100
	v_mov_b32_e32 v103, v100
	v_mov_b32_e32 v108, v100
	v_mov_b32_e32 v109, v100
	v_mfma_f32_32x32x16_bf16 v[20:35], v[112:115], v[132:135], v[20:35]
	s_nop 2
	v_mul_f32_e64 v50, v0, v50
	v_mul_f32_e64 v51, v0, v51
	v_mul_f32_e64 v48, v0, v48
	v_mul_f32_e64 v49, v0, v49
	v_mul_f32_e64 v46, v0, v46
	v_mul_f32_e64 v47, v0, v47
	v_pk_mul_f32 v[44:45], v[0:1], v[44:45] op_sel_hi:[0,1]
	v_pk_mul_f32 v[42:43], v[0:1], v[42:43] op_sel_hi:[0,1]
	v_pk_mul_f32 v[40:41], v[0:1], v[40:41] op_sel_hi:[0,1]
	v_pk_mul_f32 v[38:39], v[0:1], v[38:39] op_sel_hi:[0,1]
	s_waitcnt lgkmcnt(0)
	v_mfma_f32_32x32x16_bf16 v[4:19], v[104:107], v[132:135], v[4:19]
	v_mul_f32_e64 v36, v0, v36
	v_mul_f32_e64 v37, v0, v37
	v_mul_f32_e64 v34, v0, v34
	v_mul_f32_e64 v35, v0, v35
	v_mul_f32_e64 v32, v0, v32
	v_mul_f32_e64 v33, v0, v33
	v_pk_mul_f32 v[30:31], v[0:1], v[30:31] op_sel_hi:[0,1]
	v_pk_mul_f32 v[28:29], v[0:1], v[28:29] op_sel_hi:[0,1]
	v_pk_mul_f32 v[26:27], v[0:1], v[26:27] op_sel_hi:[0,1]
	v_pk_mul_f32 v[24:25], v[0:1], v[24:25] op_sel_hi:[0,1]
	v_pk_mul_f32 v[22:23], v[0:1], v[22:23] op_sel_hi:[0,1]
	v_pk_mul_f32 v[20:21], v[0:1], v[20:21] op_sel_hi:[0,1]
	v_pk_mul_f32 v[18:19], v[0:1], v[18:19] op_sel_hi:[0,1]
	v_pk_mul_f32 v[16:17], v[0:1], v[16:17] op_sel_hi:[0,1]
	v_pk_mul_f32 v[14:15], v[0:1], v[14:15] op_sel_hi:[0,1]
	v_pk_mul_f32 v[12:13], v[0:1], v[12:13] op_sel_hi:[0,1]
	v_pk_mul_f32 v[10:11], v[0:1], v[10:11] op_sel_hi:[0,1]
	v_pk_mul_f32 v[8:9], v[0:1], v[8:9] op_sel_hi:[0,1]
	v_pk_mul_f32 v[6:7], v[0:1], v[6:7] op_sel_hi:[0,1]
	v_pk_mul_f32 v[4:5], v[0:1], v[4:5] op_sel_hi:[0,1]
	v_mov_b32_e32 v0, v1
	v_mov_b64_e32 v[146:147], v[2:3]
	v_mov_b64_e32 v[142:143], v[2:3]
	v_mov_b64_e32 v[138:139], v[2:3]
	v_mov_b64_e32 v[134:135], v[2:3]
	v_mov_b64_e32 v[144:145], v[0:1]
	v_mov_b64_e32 v[140:141], v[0:1]
	v_mov_b64_e32 v[136:137], v[0:1]
	v_mov_b64_e32 v[132:133], v[0:1]
	v_mov_b32_e32 v104, v100
	v_mov_b32_e32 v105, v100
	v_mov_b32_e32 v106, v100
	v_mov_b32_e32 v107, v100
	v_mov_b32_e32 v110, v100
	v_mov_b32_e32 v111, v100
	v_mov_b32_e32 v112, v100
	v_mov_b32_e32 v113, v100
	v_mov_b32_e32 v114, v100
	v_mov_b32_e32 v115, v100
	s_branch .LBB0_1103
	.p2alignl 6, 3212836864

.LBB0_1101:
	s_and_b32 s6, s5, 0x6000
	v_add_u32_e32 v0, s6, v189
	ds_read_b128 v[164:167], v0
	ds_read_b128 v[208:211], v0 offset:512
	ds_read_b128 v[212:215], v0 offset:2560
	ds_read_b128 v[216:219], v0 offset:2048
	ds_read_b128 v[220:223], v0 offset:4608
	ds_read_b128 v[224:227], v0 offset:4096
	ds_read_b128 v[200:203], v0 offset:6656
	ds_read_b128 v[228:231], v0 offset:6144
	s_and_b32 s6, s3, 0xc000
	v_add_u32_e32 v177, s6, v192
	s_waitcnt lgkmcnt(7)
	v_mfma_f32_32x32x16_bf16 v[84:99], v[164:167], v[128:131], v[100:115]
	s_waitcnt lgkmcnt(6)
	v_mfma_f32_32x32x16_bf16 v[68:83], v[208:211], v[128:131], v[100:115]
	s_waitcnt lgkmcnt(5)
	v_mfma_f32_32x32x16_bf16 v[68:83], v[212:215], v[124:127], v[68:83]
	s_waitcnt lgkmcnt(4)
	v_mfma_f32_32x32x16_bf16 v[84:99], v[216:219], v[124:127], v[84:99]
	s_waitcnt lgkmcnt(3)
	v_mfma_f32_32x32x16_bf16 v[68:83], v[220:223], v[120:123], v[68:83]
	s_waitcnt lgkmcnt(2)
	v_mfma_f32_32x32x16_bf16 v[84:99], v[224:227], v[120:123], v[84:99]
	s_waitcnt lgkmcnt(1)
	v_mfma_f32_32x32x16_bf16 v[68:83], v[200:203], v[116:119], v[68:83]
	s_waitcnt lgkmcnt(0)
	v_mfma_f32_32x32x16_bf16 v[84:99], v[228:231], v[116:119], v[84:99]
	ds_read_b64_tr_b16 v[160:161], v177 offset:32768
	ds_read_b64_tr_b16 v[162:163], v177 offset:33280
	ds_read_b64_tr_b16 v[156:157], v177 offset:36864
	ds_read_b64_tr_b16 v[158:159], v177 offset:37376
	ds_read_b64_tr_b16 v[152:153], v177 offset:40960
	ds_read_b64_tr_b16 v[154:155], v177 offset:41472
	ds_read_b64_tr_b16 v[148:149], v177 offset:45056
	ds_read_b64_tr_b16 v[150:151], v177 offset:45568
	s_nop 2
	v_max_i32_e32 v2, v68, v69
	v_max3_i32 v2, v2, v70, v71
	v_max3_i32 v2, v2, v72, v73
	v_max3_i32 v2, v2, v74, v75
	v_max3_i32 v2, v2, v76, v77
	v_max3_i32 v2, v2, v78, v79
	v_max3_i32 v2, v2, v80, v81
	v_max3_i32 v0, v84, v85, v86
	v_max3_i32 v0, v0, v87, v88
	v_max3_i32 v0, v0, v89, v90
	v_max3_i32 v0, v0, v91, v92
	v_max3_i32 v0, v0, v93, v94
	v_max3_i32 v0, v0, v95, v96
	v_max3_i32 v0, v0, v97, v98
	v_max3_i32 v2, v2, v82, v83
	v_max3_i32 v0, v0, v99, v2
	v_mov_b32_e32 v2, v0
	s_waitcnt lgkmcnt(6)
	v_mfma_f32_32x32x16_bf16 v[52:67], v[160:163], v[144:147], v[52:67]
	s_nop 0
	v_permlane32_swap_b32_e32 v0, v2
	v_max_f32_e32 v0, v0, v2
	v_cmp_lt_f32_e32 vcc, s38, v0
	s_cbranch_vccnz .Ldattn_rare
.LBB0_1103:
	v_exp_f32_e32 v84, v84
	v_exp_f32_e32 v85, v85
	v_exp_f32_e32 v86, v86
	v_exp_f32_e32 v87, v87
	s_add_i32 s6, s64, 2
	s_cmp_ge_i32 s6, s54
	s_waitcnt lgkmcnt(4)
	v_mfma_f32_32x32x16_bf16 v[36:51], v[156:159], v[144:147], v[36:51]
	v_exp_f32_e32 v88, v88
	v_exp_f32_e32 v89, v89
	v_exp_f32_e32 v90, v90
	v_exp_f32_e32 v91, v91
	s_waitcnt lgkmcnt(2)
	v_mfma_f32_32x32x16_bf16 v[20:35], v[152:155], v[144:147], v[20:35]
	v_exp_f32_e32 v92, v92
	v_exp_f32_e32 v93, v93
	v_exp_f32_e32 v94, v94
	v_add_f32_e32 v232, v84, v85
	v_add_f32_e32 v233, v86, v87
	ds_read_b64_tr_b16 v[164:165], v177 offset:33792
	ds_read_b64_tr_b16 v[166:167], v177 offset:34304
	ds_read_b64_tr_b16 v[160:161], v177 offset:37888
	ds_read_b64_tr_b16 v[162:163], v177 offset:38400
	ds_read_b64_tr_b16 v[156:157], v177 offset:41984
	ds_read_b64_tr_b16 v[158:159], v177 offset:42496
	ds_read_b64_tr_b16 v[152:153], v177 offset:46080
	ds_read_b64_tr_b16 v[154:155], v177 offset:46592
	s_waitcnt lgkmcnt(8)
	v_mfma_f32_32x32x16_bf16 v[4:19], v[148:151], v[144:147], v[4:19]
	s_cbranch_scc1 .LBB0_1105
	s_and_b32 s6, s6, 3
	s_lshl_b32 s7, s6, 13
	s_add_i32 s7, s7, s52
	s_mov_b32 m0, s7
	s_nop 0
	global_load_lds_dwordx4 v[184:185], off
	s_lshl_b32 s6, s6, 14
	s_add_i32 s6, s6, s53
	s_mov_b32 m0, s6
	s_nop 0
	global_load_lds_dwordx4 v[182:183], off
	v_lshl_add_u64 v[2:3], v[182:183], 0, s[10:11]
	s_addk_i32 s6, 0x2000
	s_mov_b32 m0, s6
	s_nop 0
	global_load_lds_dwordx4 v[2:3], off
.LBB0_1105:
	v_exp_f32_e32 v95, v95
	v_exp_f32_e32 v96, v96
	v_add_f32_e32 v234, v88, v89
	v_add_f32_e32 v235, v90, v91
	v_cvt_pk_bf16_f32 v144, v84, v85
	v_cvt_pk_bf16_f32 v145, v86, v87
	s_waitcnt lgkmcnt(6)
	v_mfma_f32_32x32x16_bf16 v[52:67], v[164:167], v[140:143], v[52:67]
	v_exp_f32_e32 v97, v97
	v_exp_f32_e32 v98, v98
	v_cvt_pk_bf16_f32 v146, v88, v89
	v_cvt_pk_bf16_f32 v147, v90, v91
	v_add_f32_e32 v232, v92, v232
	v_add_f32_e32 v233, v93, v233
	ds_read_b64_tr_b16 v[84:85], v177 offset:34816
	ds_read_b64_tr_b16 v[86:87], v177 offset:35328
	s_waitcnt lgkmcnt(6)
	v_mfma_f32_32x32x16_bf16 v[36:51], v[160:163], v[140:143], v[36:51]
	v_exp_f32_e32 v99, v99
	v_exp_f32_e32 v68, v68
	v_add_f32_e32 v234, v94, v234
	v_add_f32_e32 v235, v95, v235
	v_add_f32_e32 v232, v96, v232
	s_waitcnt lgkmcnt(4)
	v_mfma_f32_32x32x16_bf16 v[20:35], v[156:159], v[140:143], v[20:35]
	v_exp_f32_e32 v69, v69
	v_exp_f32_e32 v70, v70
	v_add_f32_e32 v233, v97, v233
	v_add_f32_e32 v234, v98, v234
	v_add_f32_e32 v235, v99, v235
	s_waitcnt lgkmcnt(2)
	v_mfma_f32_32x32x16_bf16 v[4:19], v[152:155], v[140:143], v[4:19]
	v_cvt_pk_bf16_f32 v140, v92, v93
	v_cvt_pk_bf16_f32 v141, v94, v95
	v_cvt_pk_bf16_f32 v142, v96, v97
	v_cvt_pk_bf16_f32 v143, v98, v99
	v_exp_f32_e32 v71, v71
	v_exp_f32_e32 v72, v72
	ds_read_b64_tr_b16 v[88:89], v177 offset:35840
	ds_read_b64_tr_b16 v[90:91], v177 offset:36352
	s_waitcnt lgkmcnt(2)
	v_mfma_f32_32x32x16_bf16 v[52:67], v[84:87], v[136:139], v[52:67]
	v_exp_f32_e32 v73, v73
	v_exp_f32_e32 v74, v74
	v_add_f32_e32 v232, v68, v232
	v_add_f32_e32 v233, v69, v233
	v_add_f32_e32 v234, v70, v234
	ds_read_b64_tr_b16 v[84:85], v177 offset:38912
	ds_read_b64_tr_b16 v[86:87], v177 offset:39424
	ds_read_b64_tr_b16 v[92:93], v177 offset:39936
	ds_read_b64_tr_b16 v[94:95], v177 offset:40448
	ds_read_b64_tr_b16 v[96:97], v177 offset:43008
	ds_read_b64_tr_b16 v[98:99], v177 offset:43520
	ds_read_b64_tr_b16 v[148:149], v177 offset:44032
	ds_read_b64_tr_b16 v[150:151], v177 offset:44544
	s_waitcnt lgkmcnt(6)
	v_mfma_f32_32x32x16_bf16 v[36:51], v[84:87], v[136:139], v[36:51]
	v_exp_f32_e32 v75, v75
	v_exp_f32_e32 v76, v76
	v_add_f32_e32 v235, v71, v235
	v_add_f32_e32 v232, v72, v232
	v_add_f32_e32 v233, v73, v233
	ds_read_b64_tr_b16 v[84:85], v177 offset:47104
	ds_read_b64_tr_b16 v[86:87], v177 offset:47616
	ds_read_b64_tr_b16 v[152:153], v177 offset:48128
	ds_read_b64_tr_b16 v[154:155], v177 offset:48640
	s_waitcnt lgkmcnt(6)
	v_mfma_f32_32x32x16_bf16 v[20:35], v[96:99], v[136:139], v[20:35]
	v_exp_f32_e32 v77, v77
	v_exp_f32_e32 v78, v78
	v_add_f32_e32 v234, v74, v234
	v_add_f32_e32 v235, v75, v235
	v_add_f32_e32 v232, v76, v232
	s_addk_i32 s3, 0x4000
	s_addk_i32 s5, 0x2000
	s_waitcnt lgkmcnt(2)
	v_mfma_f32_32x32x16_bf16 v[4:19], v[84:87], v[136:139], v[4:19]
	v_exp_f32_e32 v79, v79
	v_exp_f32_e32 v80, v80
	v_add_f32_e32 v233, v77, v233
	v_add_f32_e32 v234, v78, v234
	v_lshl_add_u64 v[182:183], v[182:183], 0, s[14:15]
	v_mfma_f32_32x32x16_bf16 v[52:67], v[88:91], v[132:135], v[52:67]
	v_cvt_pk_bf16_f32 v136, v68, v69
	v_cvt_pk_bf16_f32 v137, v70, v71
	v_cvt_pk_bf16_f32 v138, v72, v73
	v_cvt_pk_bf16_f32 v139, v74, v75
	v_exp_f32_e32 v81, v81
	v_add_f32_e32 v235, v79, v235
	v_mfma_f32_32x32x16_bf16 v[36:51], v[92:95], v[132:135], v[36:51]
	v_exp_f32_e32 v82, v82
	v_exp_f32_e32 v83, v83
	v_add_f32_e32 v232, v80, v232
	v_add_f32_e32 v233, v81, v233
	v_lshl_add_u64 v[184:185], v[184:185], 0, s[14:15]
	v_mfma_f32_32x32x16_bf16 v[20:35], v[148:151], v[132:135], v[20:35]
	v_add_f32_e32 v234, v82, v234
	v_add_f32_e32 v235, v83, v235
	v_add_f32_e32 v232, v233, v232
	v_add_f32_e32 v234, v235, v234
	v_add_f32_e32 v232, v234, v232
	v_add_f32_e32 v173, v173, v232
	s_cmp_lg_u32 s25, s27
	s_waitcnt lgkmcnt(0)
	v_mfma_f32_32x32x16_bf16 v[4:19], v[152:155], v[132:135], v[4:19]
	v_cvt_pk_bf16_f32 v132, v76, v77
	v_cvt_pk_bf16_f32 v133, v78, v79
	v_cvt_pk_bf16_f32 v134, v80, v81
	v_cvt_pk_bf16_f32 v135, v82, v83
	s_cbranch_scc1 .LBB0_1097
	s_nop 0
	s_nop 0
	s_nop 0
	s_nop 0
	s_nop 0
	s_nop 0
	s_nop 0
	s_nop 0
	s_nop 0
	s_nop 0
	s_nop 0
	s_nop 0
	s_nop 0
	s_nop 0
	s_nop 0
	s_nop 0
